# XCD-local barrier: waiters poll the arrival counter itself (target = 32*(old/32+1)), no separate release atomic; M4' loads its norm weights before the workgroup barrier and handles 8 rows per batch
# speedup vs baseline: 1.0104x; 1.0058x over previous
; __device__ __forceinline__ unsigned xb_ld(unsigned* p)              { return __hip_atomic_load(p, __ATOMIC_RELAXED, __HIP_MEMORY_SCOPE_AGENT); }
; __device__ __forceinline__ unsigned xb_add(unsigned* p, unsigned v) { return __hip_atomic_fetch_add(p, v, __ATOMIC_RELAXED, __HIP_MEMORY_SCOPE_AGENT); }
; #define XB_SPIN(cond, bar) do { unsigned _sp = 0; while (cond) { __builtin_amdgcn_s_sleep(1); \
;     if ((++_sp & 255u) == 0u) { if (xb_ld(&(bar)[XB_TMO])) break; if (_sp > XB_SPIN_CAP) { atomicAdd(&(bar)[XB_TMO], 1u); break; } } } } while (0)
; __device__ __forceinline__ void xcd_barrier(const XcdBarrier& b) {
;     asm volatile("s_waitcnt vmcnt(0)" ::: "memory");
;     __syncthreads();
;     if (threadIdx.x == 0) {
;         unsigned* bar = b.bar;
;         __builtin_amdgcn_s_waitcnt(0);
;         unsigned nloc = b.st[0], nx = b.st[1];
;         if (nloc == 0u) { xcd_barrier_complete(bar, b.x, nloc, nx); b.st[0] = nloc; b.st[1] = nx; }
;         const unsigned old = xb_add(&bar[XB_XSUB(b.x)], 1u);
;         const unsigned gen = old / nloc;
;         if (old + 1u == (gen + 1u) * nloc) {
;             __builtin_amdgcn_fence(__ATOMIC_RELEASE, "agent");
;             asm volatile("s_waitcnt vmcnt(0)" ::: "memory");
;             const unsigned og = xb_add(&bar[XB_TOP], 1u);
;             const unsigned tg = og / nx;
;             if (og + 1u == (tg + 1u) * nx) xb_add(&bar[XB_TOPGEN], 1u);
;             else XB_SPIN(xb_ld(&bar[XB_TOPGEN]) == tg, bar);
;             __builtin_amdgcn_fence(__ATOMIC_ACQUIRE, "agent");
;             xb_add(&bar[XB_XGEN(b.x)], 1u);
;             asm volatile("s_waitcnt vmcnt(0)" ::: "memory");
;         } else {
;             XB_SPIN(xb_ld(&bar[XB_XGEN(b.x)]) == gen, bar);
;             __builtin_amdgcn_fence(__ATOMIC_ACQUIRE, "agent");
;             asm volatile("s_waitcnt vmcnt(0)" ::: "memory");
;         }
.Lfb2_fast:
	v_readlane_b32 s3, v251, 0
	s_and_b32 s6, s3, 7
	s_lshl_b32 s6, s6, 5
	s_add_u32 s8, s80, 0x10040
	s_addc_u32 s9, s81, 0
	s_add_u32 s8, s8, s6
	s_addc_u32 s9, s9, 0
	v_mov_b32_e32 v0, 0
	v_mov_b32_e32 v1, 1
	global_atomic_add v2, v0, v1, s[8:9] sc0
	s_waitcnt vmcnt(0)
	v_readfirstlane_b32 s3, v2
	s_lshr_b32 s7, s3, 5
	s_add_i32 s7, s7, 1
	s_lshl_b32 s7, s7, 5
	s_and_b32 s3, s3, 31
	s_cmp_eq_u32 s3, 31
	s_cbranch_scc0 .Lfb2_spin0
	s_branch .Lfb2_rel

; __device__ __forceinline__ unsigned xb_ld(unsigned* p)              { return __hip_atomic_load(p, __ATOMIC_RELAXED, __HIP_MEMORY_SCOPE_AGENT); }
; __device__ __forceinline__ unsigned xb_add(unsigned* p, unsigned v) { return __hip_atomic_fetch_add(p, v, __ATOMIC_RELAXED, __HIP_MEMORY_SCOPE_AGENT); }
; #define XB_SPIN(cond, bar) do { unsigned _sp = 0; while (cond) { __builtin_amdgcn_s_sleep(1); \
;     if ((++_sp & 255u) == 0u) { if (xb_ld(&(bar)[XB_TMO])) break; if (_sp > XB_SPIN_CAP) { atomicAdd(&(bar)[XB_TMO], 1u); break; } } } } while (0)
; __device__ __forceinline__ void xcd_barrier(const XcdBarrier& b) {
;     ...
;             else XB_SPIN(xb_ld(&bar[XB_TOPGEN]) == tg, bar);
;             __builtin_amdgcn_fence(__ATOMIC_ACQUIRE, "agent");
;             xb_add(&bar[XB_XGEN(b.x)], 1u);
;             asm volatile("s_waitcnt vmcnt(0)" ::: "memory");
;         } else {
;             XB_SPIN(xb_ld(&bar[XB_XGEN(b.x)]) == gen, bar);
.Lfb2_spin:
	s_sleep 1
	global_load_dword v2, v0, s[8:9] sc1
	s_add_i32 s16, s16, 1
	s_waitcnt vmcnt(0)
	v_readfirstlane_b32 s3, v2
	s_cmp_ge_u32 s3, s7
	s_cbranch_scc1 .Lfb2_rel
	s_cmp_lt_u32 s16, 0x8000
	s_cbranch_scc1 .Lfb2_spin

; DI u32x4 pack8(const float (&v)[8]) { u32x4 r; r.x = pk2(v[0], v[1]); r.y = pk2(v[2], v[3]); r.z = pk2(v[4], v[5]); r.w = pk2(v[6], v[7]); return r; }
; #define PHASE_IDS() const int tid = opaque_tid(), lane = tid & 63, r16 = lane & 15, q4 = lane >> 4; (void)r16; (void)q4; (void)tid
; __global__ void __launch_bounds__(512, 2) fwd_megakernel(Args args) {
;     ...
;             for (int m0 = gw; m0 < MTOK; m0 += 4 * NGW) {
;                 PHASE_IDS();
;                 f32x4 sv[4][3]; u32x4 yv[4][2];
;                 const int colA = lane * 8, colB = 512 + lane * 8;
; #pragma unroll
;                 for (int r = 0; r < 4; ++r) { const int m = min(m0 + r * NGW, MTOK - 1);
;                     sv[r][0] = *(const f32x4*)(mss_g + (size_t)m * 4); sv[r][1] = *(const f32x4*)(mss_g + ((size_t)MTOK + m) * 4); sv[r][2] = (f32x4){mss_a[m], mss_a[(size_t)MTOK + m], mss_a[(size_t)2 * MTOK + m], mss_a[(size_t)3 * MTOK + m]};
;                     yv[r][0] = *(const u32x4*)(Yg + (size_t)m * DM + colA); yv[r][1] = *(const u32x4*)(Yg + (size_t)m * DM + 512 + (lane & 31) * 8); }
;                 float nwA[8], nwB[8];
;                 { const float* p = args.in[12] + layer * 512 + colA;
; #pragma unroll
;                   for (int i = 0; i < 8; ++i) nwA[i] = p[i];
;                   const float* q = args.in[15] + layer * 256 + (lane & 31) * 8;
; #pragma unroll
;                   for (int i = 0; i < 8; ++i) nwB[i] = q[i]; }
; #pragma unroll
;                 for (int r = 0; r < 4; ++r) { const int m = m0 + r * NGW; if (m < MTOK) {
;                     const f32x4 s0 = sv[r][0], s1 = sv[r][1], s2 = sv[r][2];
;                     const float r_ssd = rsqrtf((((s0.x + s0.y) + (s0.z + s0.w)) + ((s1.x + s1.y) + (s1.z + s1.w))) * (1.f / 512.f) + EPS);
;                     const float r_att = rsqrtf(((s2.x + s2.y) + (s2.z + s2.w)) * (1.f / 256.f) + EPS);
;                     float v[8]; unpack8(yv[r][0], v);
; #pragma unroll
;                     for (int i = 0; i < 8; ++i) v[i] = v[i] * r_ssd * nwA[i];
;                     *(u32x4*)(ycat + (size_t)m * DM + colA) = pack8(v);
.Lm4f:
	s_waitcnt vmcnt(0) lgkmcnt(0)
	v_readlane_b32 s2, v252, 0
	v_readlane_b32 s3, v251, 0
	s_and_b32 s29, s3, 7
	s_lshl_b32 s29, s29, 5
	s_lshr_b32 s3, s3, 3
	s_add_i32 s3, s3, s29
	s_lshl_b32 s3, s3, 7
	s_lshl_b32 s29, s2, 4
	s_add_i32 s3, s3, s29
	s_lshl_b32 s29, s3, 11
	s_add_u32 s4, s80, 0xa000000
	s_addc_u32 s5, s81, 0
	s_add_u32 s4, s4, s29
	s_addc_u32 s5, s5, 0
	s_add_u32 s6, s80, 0xe000000
	s_addc_u32 s7, s81, 0
	s_add_u32 s6, s6, s29
	s_addc_u32 s7, s7, 0
	s_lshl_b32 s29, s3, 4
	s_add_u32 s8, s80, 0x300000
	s_addc_u32 s9, s81, 0
	s_add_u32 s8, s8, s29
	s_addc_u32 s9, s9, 0
	s_lshl_b32 s29, s3, 2
	s_add_u32 s12, s80, 0x400000
	s_addc_u32 s13, s81, 0
	s_add_u32 s12, s12, s29
	s_addc_u32 s13, s13, 0
	v_readlane_b32 s29, v253, 58
	v_readlane_b32 s30, v251, 33
	v_readlane_b32 s31, v251, 34
	s_lshl_b32 s10, s29, 8
	s_add_u32 s30, s30, s10
	s_addc_u32 s31, s31, 0
	v_readlane_b32 s34, v251, 39
	v_readlane_b32 s35, v251, 40
	s_lshl_b32 s10, s29, 7
	s_add_u32 s34, s34, s10
	s_addc_u32 s35, s35, 0
	v_and_b32_e32 v116, 63, v195
	v_and_b32_e32 v161, 15, v116
	v_bfe_u32 v162, v116, 4, 2
	v_lshlrev_b32_e32 v163, 17, v162
	v_lshl_add_u32 v163, v161, 2, v163
	global_load_dword v138, v163, s[12:13]
	v_lshlrev_b32_e32 v163, 5, v116
	global_load_dwordx4 v[118:121], v163, s[30:31]
	global_load_dwordx4 v[122:125], v163, s[30:31] offset:16
	v_and_b32_e32 v164, 31, v116
	v_lshlrev_b32_e32 v164, 5, v164
	global_load_dwordx4 v[126:129], v164, s[34:35]
	global_load_dwordx4 v[130:133], v164, s[34:35] offset:16
	s_barrier
	v_and_b32_e32 v163, 1, v162
	v_lshlrev_b32_e32 v163, 19, v163
	v_lshl_add_u32 v163, v161, 4, v163
	global_load_dwordx4 v[134:137], v163, s[8:9]
	v_lshlrev_b32_e32 v117, 4, v116
	v_add_u32_e32 v169, 0, v117
	global_load_dwordx4 v[170:173], v169, s[4:5]
	v_add_u32_e32 v169, 2048, v117
	global_load_dwordx4 v[174:177], v169, s[4:5]
	v_add_u32_e32 v169, 4096, v117
	global_load_dwordx4 v[178:181], v169, s[4:5]
	v_add_u32_e32 v169, 6144, v117
	global_load_dwordx4 v[182:185], v169, s[4:5]
	v_add_u32_e32 v169, 8192, v117
	global_load_dwordx4 v[186:189], v169, s[4:5]
	v_add_u32_e32 v169, 10240, v117
	global_load_dwordx4 v[202:205], v169, s[4:5]
	v_add_u32_e32 v169, 12288, v117
	global_load_dwordx4 v[206:209], v169, s[4:5]
	v_add_u32_e32 v169, 14336, v117
	global_load_dwordx4 v[210:213], v169, s[4:5]
	v_xor_b32_e32 v165, 16, v116
	v_lshlrev_b32_e32 v165, 2, v165
	v_xor_b32_e32 v166, 32, v116
	v_lshlrev_b32_e32 v166, 2, v166
	s_waitcnt vmcnt(0)
	v_add_f32_e32 v134, v134, v135
	v_add_f32_e32 v136, v136, v137
	v_add_f32_e32 v134, v134, v136
	ds_bpermute_b32 v135, v165, v134
	ds_bpermute_b32 v139, v165, v138
	s_waitcnt lgkmcnt(0)
	v_add_f32_e32 v134, v134, v135
	v_add_f32_e32 v138, v138, v139
	ds_bpermute_b32 v139, v166, v138
	v_mov_b32_e32 v167, 0x358637bd
	v_fmamk_f32 v154, v134, 0x3b000000, v167
	v_rsq_f32_e32 v154, v154
	s_waitcnt lgkmcnt(0)
	v_add_f32_e32 v138, v138, v139
	v_fmamk_f32 v160, v138, 0x3b800000, v167
	v_rsq_f32_e32 v160, v160
	s_nop 0
	v_readlane_b32 s60, v154, 0
	v_readlane_b32 s61, v154, 1
	v_readlane_b32 s62, v154, 2
	v_readlane_b32 s63, v154, 3
	v_readlane_b32 s64, v154, 4
	v_readlane_b32 s65, v154, 5
	v_readlane_b32 s66, v154, 6
	v_readlane_b32 s67, v154, 7
	v_readlane_b32 s68, v154, 8
	v_readlane_b32 s69, v154, 9
	v_readlane_b32 s70, v154, 10
	v_readlane_b32 s71, v154, 11
	v_readlane_b32 s72, v154, 12
	v_readlane_b32 s73, v154, 13
	v_readlane_b32 s74, v154, 14
	v_readlane_b32 s75, v154, 15
	v_add_u32_e32 v169, 0, v117
	v_lshlrev_b32_e32 v142, 16, v170
	v_and_b32_e32 v143, 0xffff0000, v170
	v_lshlrev_b32_e32 v144, 16, v171
	v_and_b32_e32 v145, 0xffff0000, v171
	v_lshlrev_b32_e32 v146, 16, v172
	v_and_b32_e32 v147, 0xffff0000, v172
	v_lshlrev_b32_e32 v148, 16, v173
	v_and_b32_e32 v149, 0xffff0000, v173
	v_mul_f32_e32 v142, s60, v142
	v_mul_f32_e32 v143, s60, v143
	v_mul_f32_e32 v144, s60, v144
	v_mul_f32_e32 v145, s60, v145
	v_mul_f32_e32 v146, s60, v146
	v_mul_f32_e32 v147, s60, v147
	v_mul_f32_e32 v148, s60, v148
	v_mul_f32_e32 v149, s60, v149
	v_mul_f32_e32 v142, v142, v118
	v_mul_f32_e32 v143, v143, v119
	v_mul_f32_e32 v144, v144, v120
	v_mul_f32_e32 v145, v145, v121
	v_mul_f32_e32 v146, v146, v122
	v_mul_f32_e32 v147, v147, v123
	v_mul_f32_e32 v148, v148, v124
	v_mul_f32_e32 v149, v149, v125
	v_cvt_pk_bf16_f32 v150, v142, v143
	v_cvt_pk_bf16_f32 v151, v144, v145
	v_cvt_pk_bf16_f32 v152, v146, v147
	v_cvt_pk_bf16_f32 v153, v148, v149
	global_store_dwordx4 v169, v[150:153], s[6:7] offset:0
	s_nop 1
	v_add_u32_e32 v169, 2048, v117
	v_lshlrev_b32_e32 v142, 16, v174
	v_and_b32_e32 v143, 0xffff0000, v174
	v_lshlrev_b32_e32 v144, 16, v175
	v_and_b32_e32 v145, 0xffff0000, v175
	v_lshlrev_b32_e32 v146, 16, v176
	v_and_b32_e32 v147, 0xffff0000, v176
	v_lshlrev_b32_e32 v148, 16, v177
	v_and_b32_e32 v149, 0xffff0000, v177
	v_mul_f32_e32 v142, s61, v142
	v_mul_f32_e32 v143, s61, v143
	v_mul_f32_e32 v144, s61, v144
	v_mul_f32_e32 v145, s61, v145
	v_mul_f32_e32 v146, s61, v146
	v_mul_f32_e32 v147, s61, v147
	v_mul_f32_e32 v148, s61, v148
	v_mul_f32_e32 v149, s61, v149
	v_mul_f32_e32 v142, v142, v118
	v_mul_f32_e32 v143, v143, v119
	v_mul_f32_e32 v144, v144, v120
	v_mul_f32_e32 v145, v145, v121
	v_mul_f32_e32 v146, v146, v122
	v_mul_f32_e32 v147, v147, v123
	v_mul_f32_e32 v148, v148, v124
	v_mul_f32_e32 v149, v149, v125
	v_cvt_pk_bf16_f32 v150, v142, v143
	v_cvt_pk_bf16_f32 v151, v144, v145
	v_cvt_pk_bf16_f32 v152, v146, v147
	v_cvt_pk_bf16_f32 v153, v148, v149
	global_store_dwordx4 v169, v[150:153], s[6:7] offset:0
	s_nop 1
	v_add_u32_e32 v169, 4096, v117
	v_lshlrev_b32_e32 v142, 16, v178
	v_and_b32_e32 v143, 0xffff0000, v178
; DI u32x4 pack8(const float (&v)[8]) { u32x4 r; r.x = pk2(v[0], v[1]); r.y = pk2(v[2], v[3]); r.z = pk2(v[4], v[5]); r.w = pk2(v[6], v[7]); return r; }
; __global__ void __launch_bounds__(512, 2) fwd_megakernel(Args args) {
;     ...
;                 for (int r = 0; r < 4; ++r) { const int m = min(m0 + r * NGW, MTOK - 1);
;                     sv[r][0] = *(const f32x4*)(mss_g + (size_t)m * 4); sv[r][1] = *(const f32x4*)(mss_g + ((size_t)MTOK + m) * 4); sv[r][2] = (f32x4){mss_a[m], mss_a[(size_t)MTOK + m], mss_a[(size_t)2 * MTOK + m], mss_a[(size_t)3 * MTOK + m]};
;                     yv[r][0] = *(const u32x4*)(Yg + (size_t)m * DM + colA); yv[r][1] = *(const u32x4*)(Yg + (size_t)m * DM + 512 + (lane & 31) * 8); }
;                 float nwA[8], nwB[8];
;                 { const float* p = args.in[12] + layer * 512 + colA;
; #pragma unroll
;                   for (int i = 0; i < 8; ++i) nwA[i] = p[i];
;                   const float* q = args.in[15] + layer * 256 + (lane & 31) * 8;
; #pragma unroll
;                   for (int i = 0; i < 8; ++i) nwB[i] = q[i]; }
; #pragma unroll
;                 for (int r = 0; r < 4; ++r) { const int m = m0 + r * NGW; if (m < MTOK) {
;                     const f32x4 s0 = sv[r][0], s1 = sv[r][1], s2 = sv[r][2];
;                     const float r_ssd = rsqrtf((((s0.x + s0.y) + (s0.z + s0.w)) + ((s1.x + s1.y) + (s1.z + s1.w))) * (1.f / 512.f) + EPS);
;                     const float r_att = rsqrtf(((s2.x + s2.y) + (s2.z + s2.w)) * (1.f / 256.f) + EPS);
;                     float v[8]; unpack8(yv[r][0], v);
; #pragma unroll
;                     for (int i = 0; i < 8; ++i) v[i] = v[i] * r_ssd * nwA[i];
;                     *(u32x4*)(ycat + (size_t)m * DM + colA) = pack8(v);
	v_lshlrev_b32_e32 v144, 16, v179
	v_and_b32_e32 v145, 0xffff0000, v179
	v_lshlrev_b32_e32 v146, 16, v180
	v_and_b32_e32 v147, 0xffff0000, v180
	v_lshlrev_b32_e32 v148, 16, v181
	v_and_b32_e32 v149, 0xffff0000, v181
	v_mul_f32_e32 v142, s62, v142
	v_mul_f32_e32 v143, s62, v143
	v_mul_f32_e32 v144, s62, v144
	v_mul_f32_e32 v145, s62, v145
	v_mul_f32_e32 v146, s62, v146
	v_mul_f32_e32 v147, s62, v147
	v_mul_f32_e32 v148, s62, v148
	v_mul_f32_e32 v149, s62, v149
	v_mul_f32_e32 v142, v142, v118
	v_mul_f32_e32 v143, v143, v119
	v_mul_f32_e32 v144, v144, v120
	v_mul_f32_e32 v145, v145, v121
	v_mul_f32_e32 v146, v146, v122
	v_mul_f32_e32 v147, v147, v123
	v_mul_f32_e32 v148, v148, v124
	v_mul_f32_e32 v149, v149, v125
	v_cvt_pk_bf16_f32 v150, v142, v143
	v_cvt_pk_bf16_f32 v151, v144, v145
	v_cvt_pk_bf16_f32 v152, v146, v147
	v_cvt_pk_bf16_f32 v153, v148, v149
	global_store_dwordx4 v169, v[150:153], s[6:7] offset:0
	s_nop 1
	v_add_u32_e32 v169, 6144, v117
	v_lshlrev_b32_e32 v142, 16, v182
	v_and_b32_e32 v143, 0xffff0000, v182
	v_lshlrev_b32_e32 v144, 16, v183
	v_and_b32_e32 v145, 0xffff0000, v183
	v_lshlrev_b32_e32 v146, 16, v184
	v_and_b32_e32 v147, 0xffff0000, v184
	v_lshlrev_b32_e32 v148, 16, v185
	v_and_b32_e32 v149, 0xffff0000, v185
	v_mul_f32_e32 v142, s63, v142
	v_mul_f32_e32 v143, s63, v143
	v_mul_f32_e32 v144, s63, v144
	v_mul_f32_e32 v145, s63, v145
	v_mul_f32_e32 v146, s63, v146
	v_mul_f32_e32 v147, s63, v147
	v_mul_f32_e32 v148, s63, v148
	v_mul_f32_e32 v149, s63, v149
	v_mul_f32_e32 v142, v142, v118
	v_mul_f32_e32 v143, v143, v119
	v_mul_f32_e32 v144, v144, v120
	v_mul_f32_e32 v145, v145, v121
	v_mul_f32_e32 v146, v146, v122
	v_mul_f32_e32 v147, v147, v123
	v_mul_f32_e32 v148, v148, v124
	v_mul_f32_e32 v149, v149, v125
	v_cvt_pk_bf16_f32 v150, v142, v143
	v_cvt_pk_bf16_f32 v151, v144, v145
	v_cvt_pk_bf16_f32 v152, v146, v147
	v_cvt_pk_bf16_f32 v153, v148, v149
	global_store_dwordx4 v169, v[150:153], s[6:7] offset:0
	s_nop 1
	v_add_u32_e32 v169, 8192, v117
	v_lshlrev_b32_e32 v142, 16, v186
	v_and_b32_e32 v143, 0xffff0000, v186
	v_lshlrev_b32_e32 v144, 16, v187
	v_and_b32_e32 v145, 0xffff0000, v187
	v_lshlrev_b32_e32 v146, 16, v188
	v_and_b32_e32 v147, 0xffff0000, v188
	v_lshlrev_b32_e32 v148, 16, v189
	v_and_b32_e32 v149, 0xffff0000, v189
	v_mul_f32_e32 v142, s64, v142
	v_mul_f32_e32 v143, s64, v143
	v_mul_f32_e32 v144, s64, v144
	v_mul_f32_e32 v145, s64, v145
	v_mul_f32_e32 v146, s64, v146
	v_mul_f32_e32 v147, s64, v147
	v_mul_f32_e32 v148, s64, v148
	v_mul_f32_e32 v149, s64, v149
	v_mul_f32_e32 v142, v142, v118
	v_mul_f32_e32 v143, v143, v119
	v_mul_f32_e32 v144, v144, v120
	v_mul_f32_e32 v145, v145, v121
	v_mul_f32_e32 v146, v146, v122
	v_mul_f32_e32 v147, v147, v123
	v_mul_f32_e32 v148, v148, v124
	v_mul_f32_e32 v149, v149, v125
	v_cvt_pk_bf16_f32 v150, v142, v143
	v_cvt_pk_bf16_f32 v151, v144, v145
	v_cvt_pk_bf16_f32 v152, v146, v147
	v_cvt_pk_bf16_f32 v153, v148, v149
	global_store_dwordx4 v169, v[150:153], s[6:7] offset:0
	s_nop 1
	v_add_u32_e32 v169, 10240, v117
	v_lshlrev_b32_e32 v142, 16, v202
	v_and_b32_e32 v143, 0xffff0000, v202
	v_lshlrev_b32_e32 v144, 16, v203
	v_and_b32_e32 v145, 0xffff0000, v203
	v_lshlrev_b32_e32 v146, 16, v204
	v_and_b32_e32 v147, 0xffff0000, v204
	v_lshlrev_b32_e32 v148, 16, v205
	v_and_b32_e32 v149, 0xffff0000, v205
	v_mul_f32_e32 v142, s65, v142
	v_mul_f32_e32 v143, s65, v143
	v_mul_f32_e32 v144, s65, v144
	v_mul_f32_e32 v145, s65, v145
	v_mul_f32_e32 v146, s65, v146
	v_mul_f32_e32 v147, s65, v147
	v_mul_f32_e32 v148, s65, v148
	v_mul_f32_e32 v149, s65, v149
	v_mul_f32_e32 v142, v142, v118
	v_mul_f32_e32 v143, v143, v119
	v_mul_f32_e32 v144, v144, v120
	v_mul_f32_e32 v145, v145, v121
	v_mul_f32_e32 v146, v146, v122
	v_mul_f32_e32 v147, v147, v123
	v_mul_f32_e32 v148, v148, v124
	v_mul_f32_e32 v149, v149, v125
	v_cvt_pk_bf16_f32 v150, v142, v143
	v_cvt_pk_bf16_f32 v151, v144, v145
	v_cvt_pk_bf16_f32 v152, v146, v147
	v_cvt_pk_bf16_f32 v153, v148, v149
	global_store_dwordx4 v169, v[150:153], s[6:7] offset:0
	s_nop 1
	v_add_u32_e32 v169, 12288, v117
	v_lshlrev_b32_e32 v142, 16, v206
	v_and_b32_e32 v143, 0xffff0000, v206
	v_lshlrev_b32_e32 v144, 16, v207
	v_and_b32_e32 v145, 0xffff0000, v207
	v_lshlrev_b32_e32 v146, 16, v208
	v_and_b32_e32 v147, 0xffff0000, v208
	v_lshlrev_b32_e32 v148, 16, v209
	v_and_b32_e32 v149, 0xffff0000, v209
	v_mul_f32_e32 v142, s66, v142
	v_mul_f32_e32 v143, s66, v143
	v_mul_f32_e32 v144, s66, v144
	v_mul_f32_e32 v145, s66, v145
	v_mul_f32_e32 v146, s66, v146
	v_mul_f32_e32 v147, s66, v147
	v_mul_f32_e32 v148, s66, v148
	v_mul_f32_e32 v149, s66, v149
	v_mul_f32_e32 v142, v142, v118
	v_mul_f32_e32 v143, v143, v119
	v_mul_f32_e32 v144, v144, v120
	v_mul_f32_e32 v145, v145, v121
	v_mul_f32_e32 v146, v146, v122
	v_mul_f32_e32 v147, v147, v123
	v_mul_f32_e32 v148, v148, v124
	v_mul_f32_e32 v149, v149, v125
	v_cvt_pk_bf16_f32 v150, v142, v143
	v_cvt_pk_bf16_f32 v151, v144, v145
	v_cvt_pk_bf16_f32 v152, v146, v147
	v_cvt_pk_bf16_f32 v153, v148, v149
	global_store_dwordx4 v169, v[150:153], s[6:7] offset:0
	s_nop 1
	v_add_u32_e32 v169, 14336, v117
	v_lshlrev_b32_e32 v142, 16, v210
	v_and_b32_e32 v143, 0xffff0000, v210
	v_lshlrev_b32_e32 v144, 16, v211
	v_and_b32_e32 v145, 0xffff0000, v211
	v_lshlrev_b32_e32 v146, 16, v212
	v_and_b32_e32 v147, 0xffff0000, v212
	v_lshlrev_b32_e32 v148, 16, v213
	v_and_b32_e32 v149, 0xffff0000, v213
	v_mul_f32_e32 v142, s67, v142
	v_mul_f32_e32 v143, s67, v143
	v_mul_f32_e32 v144, s67, v144
	v_mul_f32_e32 v145, s67, v145
	v_mul_f32_e32 v146, s67, v146
	v_mul_f32_e32 v147, s67, v147
	v_mul_f32_e32 v148, s67, v148
	v_mul_f32_e32 v149, s67, v149
	v_mul_f32_e32 v142, v142, v118
	v_mul_f32_e32 v143, v143, v119
	v_mul_f32_e32 v144, v144, v120
	v_mul_f32_e32 v145, v145, v121
	v_mul_f32_e32 v146, v146, v122
	v_mul_f32_e32 v147, v147, v123
	v_mul_f32_e32 v148, v148, v124
	v_mul_f32_e32 v149, v149, v125
	v_cvt_pk_bf16_f32 v150, v142, v143
	v_cvt_pk_bf16_f32 v151, v144, v145
	v_cvt_pk_bf16_f32 v152, v146, v147
	v_cvt_pk_bf16_f32 v153, v148, v149
	global_store_dwordx4 v169, v[150:153], s[6:7] offset:0
	s_nop 1
	v_add_u32_e32 v169, 16384, v117
	global_load_dwordx4 v[170:173], v169, s[4:5]
	v_add_u32_e32 v169, 18432, v117
	global_load_dwordx4 v[174:177], v169, s[4:5]
	v_add_u32_e32 v169, 20480, v117
	global_load_dwordx4 v[178:181], v169, s[4:5]
	v_add_u32_e32 v169, 22528, v117
	global_load_dwordx4 v[182:185], v169, s[4:5]
	v_add_u32_e32 v169, 24576, v117
	global_load_dwordx4 v[186:189], v169, s[4:5]
	v_add_u32_e32 v169, 26624, v117
	global_load_dwordx4 v[202:205], v169, s[4:5]
	v_add_u32_e32 v169, 28672, v117
	global_load_dwordx4 v[206:209], v169, s[4:5]
	v_add_u32_e32 v169, 30720, v117
	global_load_dwordx4 v[210:213], v169, s[4:5]
	s_waitcnt vmcnt(0)
; DI u32x4 pack8(const float (&v)[8]) { u32x4 r; r.x = pk2(v[0], v[1]); r.y = pk2(v[2], v[3]); r.z = pk2(v[4], v[5]); r.w = pk2(v[6], v[7]); return r; }
; __global__ void __launch_bounds__(512, 2) fwd_megakernel(Args args) {
;     ...
;                 for (int r = 0; r < 4; ++r) { const int m = min(m0 + r * NGW, MTOK - 1);
;                     sv[r][0] = *(const f32x4*)(mss_g + (size_t)m * 4); sv[r][1] = *(const f32x4*)(mss_g + ((size_t)MTOK + m) * 4); sv[r][2] = (f32x4){mss_a[m], mss_a[(size_t)MTOK + m], mss_a[(size_t)2 * MTOK + m], mss_a[(size_t)3 * MTOK + m]};
;                     yv[r][0] = *(const u32x4*)(Yg + (size_t)m * DM + colA); yv[r][1] = *(const u32x4*)(Yg + (size_t)m * DM + 512 + (lane & 31) * 8); }
;                 float nwA[8], nwB[8];
;                 { const float* p = args.in[12] + layer * 512 + colA;
; #pragma unroll
;                   for (int i = 0; i < 8; ++i) nwA[i] = p[i];
;                   const float* q = args.in[15] + layer * 256 + (lane & 31) * 8;
; #pragma unroll
;                   for (int i = 0; i < 8; ++i) nwB[i] = q[i]; }
; #pragma unroll
;                 for (int r = 0; r < 4; ++r) { const int m = m0 + r * NGW; if (m < MTOK) {
;                     const f32x4 s0 = sv[r][0], s1 = sv[r][1], s2 = sv[r][2];
;                     const float r_ssd = rsqrtf((((s0.x + s0.y) + (s0.z + s0.w)) + ((s1.x + s1.y) + (s1.z + s1.w))) * (1.f / 512.f) + EPS);
;                     const float r_att = rsqrtf(((s2.x + s2.y) + (s2.z + s2.w)) * (1.f / 256.f) + EPS);
;                     float v[8]; unpack8(yv[r][0], v);
; #pragma unroll
;                     for (int i = 0; i < 8; ++i) v[i] = v[i] * r_ssd * nwA[i];
;                     *(u32x4*)(ycat + (size_t)m * DM + colA) = pack8(v);
	v_add_u32_e32 v169, 16384, v117
	v_lshlrev_b32_e32 v142, 16, v170
	v_and_b32_e32 v143, 0xffff0000, v170
	v_lshlrev_b32_e32 v144, 16, v171
	v_and_b32_e32 v145, 0xffff0000, v171
	v_lshlrev_b32_e32 v146, 16, v172
	v_and_b32_e32 v147, 0xffff0000, v172
	v_lshlrev_b32_e32 v148, 16, v173
	v_and_b32_e32 v149, 0xffff0000, v173
	v_mul_f32_e32 v142, s68, v142
	v_mul_f32_e32 v143, s68, v143
	v_mul_f32_e32 v144, s68, v144
	v_mul_f32_e32 v145, s68, v145
	v_mul_f32_e32 v146, s68, v146
	v_mul_f32_e32 v147, s68, v147
	v_mul_f32_e32 v148, s68, v148
	v_mul_f32_e32 v149, s68, v149
	v_mul_f32_e32 v142, v142, v118
	v_mul_f32_e32 v143, v143, v119
	v_mul_f32_e32 v144, v144, v120
	v_mul_f32_e32 v145, v145, v121
	v_mul_f32_e32 v146, v146, v122
	v_mul_f32_e32 v147, v147, v123
	v_mul_f32_e32 v148, v148, v124
	v_mul_f32_e32 v149, v149, v125
	v_cvt_pk_bf16_f32 v150, v142, v143
	v_cvt_pk_bf16_f32 v151, v144, v145
	v_cvt_pk_bf16_f32 v152, v146, v147
	v_cvt_pk_bf16_f32 v153, v148, v149
	global_store_dwordx4 v169, v[150:153], s[6:7] offset:0
	s_nop 1
	v_add_u32_e32 v169, 18432, v117
	v_lshlrev_b32_e32 v142, 16, v174
	v_and_b32_e32 v143, 0xffff0000, v174
	v_lshlrev_b32_e32 v144, 16, v175
	v_and_b32_e32 v145, 0xffff0000, v175
	v_lshlrev_b32_e32 v146, 16, v176
	v_and_b32_e32 v147, 0xffff0000, v176
	v_lshlrev_b32_e32 v148, 16, v177
	v_and_b32_e32 v149, 0xffff0000, v177
	v_mul_f32_e32 v142, s69, v142
	v_mul_f32_e32 v143, s69, v143
	v_mul_f32_e32 v144, s69, v144
	v_mul_f32_e32 v145, s69, v145
	v_mul_f32_e32 v146, s69, v146
	v_mul_f32_e32 v147, s69, v147
	v_mul_f32_e32 v148, s69, v148
	v_mul_f32_e32 v149, s69, v149
	v_mul_f32_e32 v142, v142, v118
	v_mul_f32_e32 v143, v143, v119
	v_mul_f32_e32 v144, v144, v120
	v_mul_f32_e32 v145, v145, v121
	v_mul_f32_e32 v146, v146, v122
	v_mul_f32_e32 v147, v147, v123
	v_mul_f32_e32 v148, v148, v124
	v_mul_f32_e32 v149, v149, v125
	v_cvt_pk_bf16_f32 v150, v142, v143
	v_cvt_pk_bf16_f32 v151, v144, v145
	v_cvt_pk_bf16_f32 v152, v146, v147
	v_cvt_pk_bf16_f32 v153, v148, v149
	global_store_dwordx4 v169, v[150:153], s[6:7] offset:0
	s_nop 1
	v_add_u32_e32 v169, 20480, v117
	v_lshlrev_b32_e32 v142, 16, v178
	v_and_b32_e32 v143, 0xffff0000, v178
	v_lshlrev_b32_e32 v144, 16, v179
	v_and_b32_e32 v145, 0xffff0000, v179
	v_lshlrev_b32_e32 v146, 16, v180
	v_and_b32_e32 v147, 0xffff0000, v180
	v_lshlrev_b32_e32 v148, 16, v181
	v_and_b32_e32 v149, 0xffff0000, v181
	v_mul_f32_e32 v142, s70, v142
	v_mul_f32_e32 v143, s70, v143
	v_mul_f32_e32 v144, s70, v144
	v_mul_f32_e32 v145, s70, v145
	v_mul_f32_e32 v146, s70, v146
	v_mul_f32_e32 v147, s70, v147
	v_mul_f32_e32 v148, s70, v148
	v_mul_f32_e32 v149, s70, v149
	v_mul_f32_e32 v142, v142, v118
	v_mul_f32_e32 v143, v143, v119
	v_mul_f32_e32 v144, v144, v120
	v_mul_f32_e32 v145, v145, v121
	v_mul_f32_e32 v146, v146, v122
	v_mul_f32_e32 v147, v147, v123
	v_mul_f32_e32 v148, v148, v124
	v_mul_f32_e32 v149, v149, v125
	v_cvt_pk_bf16_f32 v150, v142, v143
	v_cvt_pk_bf16_f32 v151, v144, v145
	v_cvt_pk_bf16_f32 v152, v146, v147
	v_cvt_pk_bf16_f32 v153, v148, v149
	global_store_dwordx4 v169, v[150:153], s[6:7] offset:0
	s_nop 1
	v_add_u32_e32 v169, 22528, v117
	v_lshlrev_b32_e32 v142, 16, v182
	v_and_b32_e32 v143, 0xffff0000, v182
	v_lshlrev_b32_e32 v144, 16, v183
	v_and_b32_e32 v145, 0xffff0000, v183
	v_lshlrev_b32_e32 v146, 16, v184
	v_and_b32_e32 v147, 0xffff0000, v184
	v_lshlrev_b32_e32 v148, 16, v185
	v_and_b32_e32 v149, 0xffff0000, v185
	v_mul_f32_e32 v142, s71, v142
	v_mul_f32_e32 v143, s71, v143
	v_mul_f32_e32 v144, s71, v144
	v_mul_f32_e32 v145, s71, v145
	v_mul_f32_e32 v146, s71, v146
	v_mul_f32_e32 v147, s71, v147
	v_mul_f32_e32 v148, s71, v148
	v_mul_f32_e32 v149, s71, v149
	v_mul_f32_e32 v142, v142, v118
	v_mul_f32_e32 v143, v143, v119
	v_mul_f32_e32 v144, v144, v120
	v_mul_f32_e32 v145, v145, v121
	v_mul_f32_e32 v146, v146, v122
	v_mul_f32_e32 v147, v147, v123
	v_mul_f32_e32 v148, v148, v124
	v_mul_f32_e32 v149, v149, v125
	v_cvt_pk_bf16_f32 v150, v142, v143
	v_cvt_pk_bf16_f32 v151, v144, v145
	v_cvt_pk_bf16_f32 v152, v146, v147
	v_cvt_pk_bf16_f32 v153, v148, v149
	global_store_dwordx4 v169, v[150:153], s[6:7] offset:0
	s_nop 1
	v_add_u32_e32 v169, 24576, v117
	v_lshlrev_b32_e32 v142, 16, v186
	v_and_b32_e32 v143, 0xffff0000, v186
	v_lshlrev_b32_e32 v144, 16, v187
	v_and_b32_e32 v145, 0xffff0000, v187
	v_lshlrev_b32_e32 v146, 16, v188
	v_and_b32_e32 v147, 0xffff0000, v188
	v_lshlrev_b32_e32 v148, 16, v189
	v_and_b32_e32 v149, 0xffff0000, v189
	v_mul_f32_e32 v142, s72, v142
	v_mul_f32_e32 v143, s72, v143
	v_mul_f32_e32 v144, s72, v144
	v_mul_f32_e32 v145, s72, v145
	v_mul_f32_e32 v146, s72, v146
	v_mul_f32_e32 v147, s72, v147
	v_mul_f32_e32 v148, s72, v148
	v_mul_f32_e32 v149, s72, v149
	v_mul_f32_e32 v142, v142, v118
	v_mul_f32_e32 v143, v143, v119
	v_mul_f32_e32 v144, v144, v120
	v_mul_f32_e32 v145, v145, v121
	v_mul_f32_e32 v146, v146, v122
	v_mul_f32_e32 v147, v147, v123
	v_mul_f32_e32 v148, v148, v124
	v_mul_f32_e32 v149, v149, v125
	v_cvt_pk_bf16_f32 v150, v142, v143
	v_cvt_pk_bf16_f32 v151, v144, v145
	v_cvt_pk_bf16_f32 v152, v146, v147
	v_cvt_pk_bf16_f32 v153, v148, v149
	global_store_dwordx4 v169, v[150:153], s[6:7] offset:0
	s_nop 1
	v_add_u32_e32 v169, 26624, v117
	v_lshlrev_b32_e32 v142, 16, v202
	v_and_b32_e32 v143, 0xffff0000, v202
	v_lshlrev_b32_e32 v144, 16, v203
	v_and_b32_e32 v145, 0xffff0000, v203
	v_lshlrev_b32_e32 v146, 16, v204
	v_and_b32_e32 v147, 0xffff0000, v204
	v_lshlrev_b32_e32 v148, 16, v205
	v_and_b32_e32 v149, 0xffff0000, v205
	v_mul_f32_e32 v142, s73, v142
	v_mul_f32_e32 v143, s73, v143
	v_mul_f32_e32 v144, s73, v144
	v_mul_f32_e32 v145, s73, v145
	v_mul_f32_e32 v146, s73, v146
; DI u32x4 pack8(const float (&v)[8]) { u32x4 r; r.x = pk2(v[0], v[1]); r.y = pk2(v[2], v[3]); r.z = pk2(v[4], v[5]); r.w = pk2(v[6], v[7]); return r; }
; __global__ void __launch_bounds__(512, 2) fwd_megakernel(Args args) {
;     ...
;                 for (int r = 0; r < 4; ++r) { const int m = min(m0 + r * NGW, MTOK - 1);
;                     sv[r][0] = *(const f32x4*)(mss_g + (size_t)m * 4); sv[r][1] = *(const f32x4*)(mss_g + ((size_t)MTOK + m) * 4); sv[r][2] = (f32x4){mss_a[m], mss_a[(size_t)MTOK + m], mss_a[(size_t)2 * MTOK + m], mss_a[(size_t)3 * MTOK + m]};
;                     yv[r][0] = *(const u32x4*)(Yg + (size_t)m * DM + colA); yv[r][1] = *(const u32x4*)(Yg + (size_t)m * DM + 512 + (lane & 31) * 8); }
;                 float nwA[8], nwB[8];
;                 { const float* p = args.in[12] + layer * 512 + colA;
; #pragma unroll
;                   for (int i = 0; i < 8; ++i) nwA[i] = p[i];
;                   const float* q = args.in[15] + layer * 256 + (lane & 31) * 8;
; #pragma unroll
;                   for (int i = 0; i < 8; ++i) nwB[i] = q[i]; }
; #pragma unroll
;                 for (int r = 0; r < 4; ++r) { const int m = m0 + r * NGW; if (m < MTOK) {
;                     const f32x4 s0 = sv[r][0], s1 = sv[r][1], s2 = sv[r][2];
;                     const float r_ssd = rsqrtf((((s0.x + s0.y) + (s0.z + s0.w)) + ((s1.x + s1.y) + (s1.z + s1.w))) * (1.f / 512.f) + EPS);
;                     const float r_att = rsqrtf(((s2.x + s2.y) + (s2.z + s2.w)) * (1.f / 256.f) + EPS);
;                     float v[8]; unpack8(yv[r][0], v);
; #pragma unroll
;                     for (int i = 0; i < 8; ++i) v[i] = v[i] * r_ssd * nwA[i];
;                     *(u32x4*)(ycat + (size_t)m * DM + colA) = pack8(v);
;                     if (lane < 32) { unpack8(yv[r][1], v);
; #pragma unroll
;                         for (int i = 0; i < 8; ++i) v[i] = v[i] * r_att * nwB[i];
;                         *(u32x4*)(ycat + (size_t)m * DM + colB) = pack8(v); } } }
	v_mul_f32_e32 v147, s73, v147
	v_mul_f32_e32 v148, s73, v148
	v_mul_f32_e32 v149, s73, v149
	v_mul_f32_e32 v142, v142, v118
	v_mul_f32_e32 v143, v143, v119
	v_mul_f32_e32 v144, v144, v120
	v_mul_f32_e32 v145, v145, v121
	v_mul_f32_e32 v146, v146, v122
	v_mul_f32_e32 v147, v147, v123
	v_mul_f32_e32 v148, v148, v124
	v_mul_f32_e32 v149, v149, v125
	v_cvt_pk_bf16_f32 v150, v142, v143
	v_cvt_pk_bf16_f32 v151, v144, v145
	v_cvt_pk_bf16_f32 v152, v146, v147
	v_cvt_pk_bf16_f32 v153, v148, v149
	global_store_dwordx4 v169, v[150:153], s[6:7] offset:0
	s_nop 1
	v_add_u32_e32 v169, 28672, v117
	v_lshlrev_b32_e32 v142, 16, v206
	v_and_b32_e32 v143, 0xffff0000, v206
	v_lshlrev_b32_e32 v144, 16, v207
	v_and_b32_e32 v145, 0xffff0000, v207
	v_lshlrev_b32_e32 v146, 16, v208
	v_and_b32_e32 v147, 0xffff0000, v208
	v_lshlrev_b32_e32 v148, 16, v209
	v_and_b32_e32 v149, 0xffff0000, v209
	v_mul_f32_e32 v142, s74, v142
	v_mul_f32_e32 v143, s74, v143
	v_mul_f32_e32 v144, s74, v144
	v_mul_f32_e32 v145, s74, v145
	v_mul_f32_e32 v146, s74, v146
	v_mul_f32_e32 v147, s74, v147
	v_mul_f32_e32 v148, s74, v148
	v_mul_f32_e32 v149, s74, v149
	v_mul_f32_e32 v142, v142, v118
	v_mul_f32_e32 v143, v143, v119
	v_mul_f32_e32 v144, v144, v120
	v_mul_f32_e32 v145, v145, v121
	v_mul_f32_e32 v146, v146, v122
	v_mul_f32_e32 v147, v147, v123
	v_mul_f32_e32 v148, v148, v124
	v_mul_f32_e32 v149, v149, v125
	v_cvt_pk_bf16_f32 v150, v142, v143
	v_cvt_pk_bf16_f32 v151, v144, v145
	v_cvt_pk_bf16_f32 v152, v146, v147
	v_cvt_pk_bf16_f32 v153, v148, v149
	global_store_dwordx4 v169, v[150:153], s[6:7] offset:0
	s_nop 1
	v_add_u32_e32 v169, 30720, v117
	v_lshlrev_b32_e32 v142, 16, v210
	v_and_b32_e32 v143, 0xffff0000, v210
	v_lshlrev_b32_e32 v144, 16, v211
	v_and_b32_e32 v145, 0xffff0000, v211
	v_lshlrev_b32_e32 v146, 16, v212
	v_and_b32_e32 v147, 0xffff0000, v212
	v_lshlrev_b32_e32 v148, 16, v213
	v_and_b32_e32 v149, 0xffff0000, v213
	v_mul_f32_e32 v142, s75, v142
	v_mul_f32_e32 v143, s75, v143
	v_mul_f32_e32 v144, s75, v144
	v_mul_f32_e32 v145, s75, v145
	v_mul_f32_e32 v146, s75, v146
	v_mul_f32_e32 v147, s75, v147
	v_mul_f32_e32 v148, s75, v148
	v_mul_f32_e32 v149, s75, v149
	v_mul_f32_e32 v142, v142, v118
	v_mul_f32_e32 v143, v143, v119
	v_mul_f32_e32 v144, v144, v120
	v_mul_f32_e32 v145, v145, v121
	v_mul_f32_e32 v146, v146, v122
	v_mul_f32_e32 v147, v147, v123
	v_mul_f32_e32 v148, v148, v124
	v_mul_f32_e32 v149, v149, v125
	v_cvt_pk_bf16_f32 v150, v142, v143
	v_cvt_pk_bf16_f32 v151, v144, v145
	v_cvt_pk_bf16_f32 v152, v146, v147
	v_cvt_pk_bf16_f32 v153, v148, v149
	global_store_dwordx4 v169, v[150:153], s[6:7] offset:0
	s_nop 1
	v_lshrrev_b32_e32 v162, 5, v116
	v_and_b32_e32 v164, 31, v116
	v_lshlrev_b32_e32 v164, 4, v164
	v_lshl_add_u32 v164, v162, 11, v164
	v_add_u32_e32 v164, 0x400, v164
	v_add_u32_e32 v169, 0, v164
	global_load_dwordx4 v[170:173], v169, s[4:5]
	v_add_u32_e32 v169, 4096, v164
	global_load_dwordx4 v[174:177], v169, s[4:5]
	v_add_u32_e32 v169, 8192, v164
	global_load_dwordx4 v[178:181], v169, s[4:5]
	v_add_u32_e32 v169, 12288, v164
	global_load_dwordx4 v[182:185], v169, s[4:5]
	v_add_u32_e32 v169, 16384, v164
	global_load_dwordx4 v[186:189], v169, s[4:5]
	v_add_u32_e32 v169, 20480, v164
	global_load_dwordx4 v[202:205], v169, s[4:5]
	v_add_u32_e32 v169, 24576, v164
	global_load_dwordx4 v[206:209], v169, s[4:5]
	v_add_u32_e32 v169, 28672, v164
	global_load_dwordx4 v[210:213], v169, s[4:5]
	v_add_u32_e32 v163, 0, v162
	v_lshlrev_b32_e32 v163, 2, v163
	ds_bpermute_b32 v168, v163, v160
	s_waitcnt vmcnt(0) lgkmcnt(0)
	v_add_u32_e32 v169, 0, v164
	v_lshlrev_b32_e32 v142, 16, v170
	v_and_b32_e32 v143, 0xffff0000, v170
	v_lshlrev_b32_e32 v144, 16, v171
	v_and_b32_e32 v145, 0xffff0000, v171
	v_lshlrev_b32_e32 v146, 16, v172
	v_and_b32_e32 v147, 0xffff0000, v172
	v_lshlrev_b32_e32 v148, 16, v173
	v_and_b32_e32 v149, 0xffff0000, v173
	v_mul_f32_e32 v142, v142, v168
	v_mul_f32_e32 v143, v143, v168
	v_mul_f32_e32 v144, v144, v168
	v_mul_f32_e32 v145, v145, v168
	v_mul_f32_e32 v146, v146, v168
	v_mul_f32_e32 v147, v147, v168
	v_mul_f32_e32 v148, v148, v168
	v_mul_f32_e32 v149, v149, v168
	v_mul_f32_e32 v142, v142, v126
	v_mul_f32_e32 v143, v143, v127
	v_mul_f32_e32 v144, v144, v128
	v_mul_f32_e32 v145, v145, v129
	v_mul_f32_e32 v146, v146, v130
	v_mul_f32_e32 v147, v147, v131
	v_mul_f32_e32 v148, v148, v132
	v_mul_f32_e32 v149, v149, v133
	v_cvt_pk_bf16_f32 v150, v142, v143
	v_cvt_pk_bf16_f32 v151, v144, v145
	v_cvt_pk_bf16_f32 v152, v146, v147
	v_cvt_pk_bf16_f32 v153, v148, v149
	global_store_dwordx4 v169, v[150:153], s[6:7] offset:0
	s_nop 1
	v_add_u32_e32 v163, 2, v162
	v_lshlrev_b32_e32 v163, 2, v163
	ds_bpermute_b32 v168, v163, v160
	s_waitcnt lgkmcnt(0)
	v_add_u32_e32 v169, 4096, v164
	v_lshlrev_b32_e32 v142, 16, v174
	v_and_b32_e32 v143, 0xffff0000, v174
	v_lshlrev_b32_e32 v144, 16, v175
	v_and_b32_e32 v145, 0xffff0000, v175
	v_lshlrev_b32_e32 v146, 16, v176
	v_and_b32_e32 v147, 0xffff0000, v176
	v_lshlrev_b32_e32 v148, 16, v177
	v_and_b32_e32 v149, 0xffff0000, v177
	v_mul_f32_e32 v142, v142, v168
	v_mul_f32_e32 v143, v143, v168
	v_mul_f32_e32 v144, v144, v168
	v_mul_f32_e32 v145, v145, v168
	v_mul_f32_e32 v146, v146, v168
	v_mul_f32_e32 v147, v147, v168
	v_mul_f32_e32 v148, v148, v168
	v_mul_f32_e32 v149, v149, v168
	v_mul_f32_e32 v142, v142, v126
	v_mul_f32_e32 v143, v143, v127
	v_mul_f32_e32 v144, v144, v128
	v_mul_f32_e32 v145, v145, v129
	v_mul_f32_e32 v146, v146, v130
	v_mul_f32_e32 v147, v147, v131
	v_mul_f32_e32 v148, v148, v132
	v_mul_f32_e32 v149, v149, v133
	v_cvt_pk_bf16_f32 v150, v142, v143
	v_cvt_pk_bf16_f32 v151, v144, v145
	v_cvt_pk_bf16_f32 v152, v146, v147
	v_cvt_pk_bf16_f32 v153, v148, v149
	global_store_dwordx4 v169, v[150:153], s[6:7] offset:0
	s_nop 1
	v_add_u32_e32 v163, 4, v162
	v_lshlrev_b32_e32 v163, 2, v163
	ds_bpermute_b32 v168, v163, v160
	s_waitcnt lgkmcnt(0)
; DI u32x4 pack8(const float (&v)[8]) { u32x4 r; r.x = pk2(v[0], v[1]); r.y = pk2(v[2], v[3]); r.z = pk2(v[4], v[5]); r.w = pk2(v[6], v[7]); return r; }
; __global__ void __launch_bounds__(512, 2) fwd_megakernel(Args args) {
;     ...
;                     yv[r][0] = *(const u32x4*)(Yg + (size_t)m * DM + colA); yv[r][1] = *(const u32x4*)(Yg + (size_t)m * DM + 512 + (lane & 31) * 8); }
;                 float nwA[8], nwB[8];
;                 { const float* p = args.in[12] + layer * 512 + colA;
; #pragma unroll
;                   for (int i = 0; i < 8; ++i) nwA[i] = p[i];
;                   const float* q = args.in[15] + layer * 256 + (lane & 31) * 8;
; #pragma unroll
;                   for (int i = 0; i < 8; ++i) nwB[i] = q[i]; }
; #pragma unroll
;                 for (int r = 0; r < 4; ++r) { const int m = m0 + r * NGW; if (m < MTOK) {
;                     const f32x4 s0 = sv[r][0], s1 = sv[r][1], s2 = sv[r][2];
;                     const float r_ssd = rsqrtf((((s0.x + s0.y) + (s0.z + s0.w)) + ((s1.x + s1.y) + (s1.z + s1.w))) * (1.f / 512.f) + EPS);
;                     const float r_att = rsqrtf(((s2.x + s2.y) + (s2.z + s2.w)) * (1.f / 256.f) + EPS);
;                     float v[8]; unpack8(yv[r][0], v);
; #pragma unroll
;                     for (int i = 0; i < 8; ++i) v[i] = v[i] * r_ssd * nwA[i];
;                     *(u32x4*)(ycat + (size_t)m * DM + colA) = pack8(v);
;                     if (lane < 32) { unpack8(yv[r][1], v);
; #pragma unroll
;                         for (int i = 0; i < 8; ++i) v[i] = v[i] * r_att * nwB[i];
;                         *(u32x4*)(ycat + (size_t)m * DM + colB) = pack8(v); } } }
	v_add_u32_e32 v169, 8192, v164
	v_lshlrev_b32_e32 v142, 16, v178
	v_and_b32_e32 v143, 0xffff0000, v178
	v_lshlrev_b32_e32 v144, 16, v179
	v_and_b32_e32 v145, 0xffff0000, v179
	v_lshlrev_b32_e32 v146, 16, v180
	v_and_b32_e32 v147, 0xffff0000, v180
	v_lshlrev_b32_e32 v148, 16, v181
	v_and_b32_e32 v149, 0xffff0000, v181
	v_mul_f32_e32 v142, v142, v168
	v_mul_f32_e32 v143, v143, v168
	v_mul_f32_e32 v144, v144, v168
	v_mul_f32_e32 v145, v145, v168
	v_mul_f32_e32 v146, v146, v168
	v_mul_f32_e32 v147, v147, v168
	v_mul_f32_e32 v148, v148, v168
	v_mul_f32_e32 v149, v149, v168
	v_mul_f32_e32 v142, v142, v126
	v_mul_f32_e32 v143, v143, v127
	v_mul_f32_e32 v144, v144, v128
	v_mul_f32_e32 v145, v145, v129
	v_mul_f32_e32 v146, v146, v130
	v_mul_f32_e32 v147, v147, v131
	v_mul_f32_e32 v148, v148, v132
	v_mul_f32_e32 v149, v149, v133
	v_cvt_pk_bf16_f32 v150, v142, v143
	v_cvt_pk_bf16_f32 v151, v144, v145
	v_cvt_pk_bf16_f32 v152, v146, v147
	v_cvt_pk_bf16_f32 v153, v148, v149
	global_store_dwordx4 v169, v[150:153], s[6:7] offset:0
	s_nop 1
	v_add_u32_e32 v163, 6, v162
	v_lshlrev_b32_e32 v163, 2, v163
	ds_bpermute_b32 v168, v163, v160
	s_waitcnt lgkmcnt(0)
	v_add_u32_e32 v169, 12288, v164
	v_lshlrev_b32_e32 v142, 16, v182
	v_and_b32_e32 v143, 0xffff0000, v182
	v_lshlrev_b32_e32 v144, 16, v183
	v_and_b32_e32 v145, 0xffff0000, v183
	v_lshlrev_b32_e32 v146, 16, v184
	v_and_b32_e32 v147, 0xffff0000, v184
	v_lshlrev_b32_e32 v148, 16, v185
	v_and_b32_e32 v149, 0xffff0000, v185
	v_mul_f32_e32 v142, v142, v168
	v_mul_f32_e32 v143, v143, v168
	v_mul_f32_e32 v144, v144, v168
	v_mul_f32_e32 v145, v145, v168
	v_mul_f32_e32 v146, v146, v168
	v_mul_f32_e32 v147, v147, v168
	v_mul_f32_e32 v148, v148, v168
	v_mul_f32_e32 v149, v149, v168
	v_mul_f32_e32 v142, v142, v126
	v_mul_f32_e32 v143, v143, v127
	v_mul_f32_e32 v144, v144, v128
	v_mul_f32_e32 v145, v145, v129
	v_mul_f32_e32 v146, v146, v130
	v_mul_f32_e32 v147, v147, v131
	v_mul_f32_e32 v148, v148, v132
	v_mul_f32_e32 v149, v149, v133
	v_cvt_pk_bf16_f32 v150, v142, v143
	v_cvt_pk_bf16_f32 v151, v144, v145
	v_cvt_pk_bf16_f32 v152, v146, v147
	v_cvt_pk_bf16_f32 v153, v148, v149
	global_store_dwordx4 v169, v[150:153], s[6:7] offset:0
	s_nop 1
	v_add_u32_e32 v163, 8, v162
	v_lshlrev_b32_e32 v163, 2, v163
	ds_bpermute_b32 v168, v163, v160
	s_waitcnt lgkmcnt(0)
	v_add_u32_e32 v169, 16384, v164
	v_lshlrev_b32_e32 v142, 16, v186
	v_and_b32_e32 v143, 0xffff0000, v186
	v_lshlrev_b32_e32 v144, 16, v187
	v_and_b32_e32 v145, 0xffff0000, v187
	v_lshlrev_b32_e32 v146, 16, v188
	v_and_b32_e32 v147, 0xffff0000, v188
	v_lshlrev_b32_e32 v148, 16, v189
	v_and_b32_e32 v149, 0xffff0000, v189
	v_mul_f32_e32 v142, v142, v168
	v_mul_f32_e32 v143, v143, v168
	v_mul_f32_e32 v144, v144, v168
	v_mul_f32_e32 v145, v145, v168
	v_mul_f32_e32 v146, v146, v168
	v_mul_f32_e32 v147, v147, v168
	v_mul_f32_e32 v148, v148, v168
	v_mul_f32_e32 v149, v149, v168
	v_mul_f32_e32 v142, v142, v126
	v_mul_f32_e32 v143, v143, v127
	v_mul_f32_e32 v144, v144, v128
	v_mul_f32_e32 v145, v145, v129
	v_mul_f32_e32 v146, v146, v130
	v_mul_f32_e32 v147, v147, v131
	v_mul_f32_e32 v148, v148, v132
	v_mul_f32_e32 v149, v149, v133
	v_cvt_pk_bf16_f32 v150, v142, v143
	v_cvt_pk_bf16_f32 v151, v144, v145
	v_cvt_pk_bf16_f32 v152, v146, v147
	v_cvt_pk_bf16_f32 v153, v148, v149
	global_store_dwordx4 v169, v[150:153], s[6:7] offset:0
	s_nop 1
	v_add_u32_e32 v163, 10, v162
	v_lshlrev_b32_e32 v163, 2, v163
	ds_bpermute_b32 v168, v163, v160
	s_waitcnt lgkmcnt(0)
; DI u32x4 pack8(const float (&v)[8]) { u32x4 r; r.x = pk2(v[0], v[1]); r.y = pk2(v[2], v[3]); r.z = pk2(v[4], v[5]); r.w = pk2(v[6], v[7]); return r; }
; __global__ void __launch_bounds__(512, 2) fwd_megakernel(Args args) {
;     ...
;             for (int m0 = gw; m0 < MTOK; m0 += 4 * NGW) {
;     ...
;                     yv[r][0] = *(const u32x4*)(Yg + (size_t)m * DM + colA); yv[r][1] = *(const u32x4*)(Yg + (size_t)m * DM + 512 + (lane & 31) * 8); }
;                 float nwA[8], nwB[8];
;                 { const float* p = args.in[12] + layer * 512 + colA;
; #pragma unroll
;                   for (int i = 0; i < 8; ++i) nwA[i] = p[i];
;                   const float* q = args.in[15] + layer * 256 + (lane & 31) * 8;
; #pragma unroll
;                   for (int i = 0; i < 8; ++i) nwB[i] = q[i]; }
; #pragma unroll
;                 for (int r = 0; r < 4; ++r) { const int m = m0 + r * NGW; if (m < MTOK) {
;                     const f32x4 s0 = sv[r][0], s1 = sv[r][1], s2 = sv[r][2];
;                     const float r_ssd = rsqrtf((((s0.x + s0.y) + (s0.z + s0.w)) + ((s1.x + s1.y) + (s1.z + s1.w))) * (1.f / 512.f) + EPS);
;                     const float r_att = rsqrtf(((s2.x + s2.y) + (s2.z + s2.w)) * (1.f / 256.f) + EPS);
;                     float v[8]; unpack8(yv[r][0], v);
; #pragma unroll
;                     for (int i = 0; i < 8; ++i) v[i] = v[i] * r_ssd * nwA[i];
;                     *(u32x4*)(ycat + (size_t)m * DM + colA) = pack8(v);
;                     if (lane < 32) { unpack8(yv[r][1], v);
; #pragma unroll
;                         for (int i = 0; i < 8; ++i) v[i] = v[i] * r_att * nwB[i];
;                         *(u32x4*)(ycat + (size_t)m * DM + colB) = pack8(v); } } }
	v_add_u32_e32 v169, 20480, v164
	v_lshlrev_b32_e32 v142, 16, v202
	v_and_b32_e32 v143, 0xffff0000, v202
	v_lshlrev_b32_e32 v144, 16, v203
	v_and_b32_e32 v145, 0xffff0000, v203
	v_lshlrev_b32_e32 v146, 16, v204
	v_and_b32_e32 v147, 0xffff0000, v204
	v_lshlrev_b32_e32 v148, 16, v205
	v_and_b32_e32 v149, 0xffff0000, v205
	v_mul_f32_e32 v142, v142, v168
	v_mul_f32_e32 v143, v143, v168
	v_mul_f32_e32 v144, v144, v168
	v_mul_f32_e32 v145, v145, v168
	v_mul_f32_e32 v146, v146, v168
	v_mul_f32_e32 v147, v147, v168
	v_mul_f32_e32 v148, v148, v168
	v_mul_f32_e32 v149, v149, v168
	v_mul_f32_e32 v142, v142, v126
	v_mul_f32_e32 v143, v143, v127
	v_mul_f32_e32 v144, v144, v128
	v_mul_f32_e32 v145, v145, v129
	v_mul_f32_e32 v146, v146, v130
	v_mul_f32_e32 v147, v147, v131
	v_mul_f32_e32 v148, v148, v132
	v_mul_f32_e32 v149, v149, v133
	v_cvt_pk_bf16_f32 v150, v142, v143
	v_cvt_pk_bf16_f32 v151, v144, v145
	v_cvt_pk_bf16_f32 v152, v146, v147
	v_cvt_pk_bf16_f32 v153, v148, v149
	global_store_dwordx4 v169, v[150:153], s[6:7] offset:0
	s_nop 1
	v_add_u32_e32 v163, 12, v162
	v_lshlrev_b32_e32 v163, 2, v163
	ds_bpermute_b32 v168, v163, v160
	s_waitcnt lgkmcnt(0)
	v_add_u32_e32 v169, 24576, v164
	v_lshlrev_b32_e32 v142, 16, v206
	v_and_b32_e32 v143, 0xffff0000, v206
	v_lshlrev_b32_e32 v144, 16, v207
	v_and_b32_e32 v145, 0xffff0000, v207
	v_lshlrev_b32_e32 v146, 16, v208
	v_and_b32_e32 v147, 0xffff0000, v208
	v_lshlrev_b32_e32 v148, 16, v209
	v_and_b32_e32 v149, 0xffff0000, v209
	v_mul_f32_e32 v142, v142, v168
	v_mul_f32_e32 v143, v143, v168
	v_mul_f32_e32 v144, v144, v168
	v_mul_f32_e32 v145, v145, v168
	v_mul_f32_e32 v146, v146, v168
	v_mul_f32_e32 v147, v147, v168
	v_mul_f32_e32 v148, v148, v168
	v_mul_f32_e32 v149, v149, v168
	v_mul_f32_e32 v142, v142, v126
	v_mul_f32_e32 v143, v143, v127
	v_mul_f32_e32 v144, v144, v128
	v_mul_f32_e32 v145, v145, v129
	v_mul_f32_e32 v146, v146, v130
	v_mul_f32_e32 v147, v147, v131
	v_mul_f32_e32 v148, v148, v132
	v_mul_f32_e32 v149, v149, v133
	v_cvt_pk_bf16_f32 v150, v142, v143
	v_cvt_pk_bf16_f32 v151, v144, v145
	v_cvt_pk_bf16_f32 v152, v146, v147
	v_cvt_pk_bf16_f32 v153, v148, v149
	global_store_dwordx4 v169, v[150:153], s[6:7] offset:0
	s_nop 1
	v_add_u32_e32 v163, 14, v162
	v_lshlrev_b32_e32 v163, 2, v163
	ds_bpermute_b32 v168, v163, v160
	s_waitcnt lgkmcnt(0)
	v_add_u32_e32 v169, 28672, v164
	v_lshlrev_b32_e32 v142, 16, v210
	v_and_b32_e32 v143, 0xffff0000, v210
	v_lshlrev_b32_e32 v144, 16, v211
	v_and_b32_e32 v145, 0xffff0000, v211
	v_lshlrev_b32_e32 v146, 16, v212
	v_and_b32_e32 v147, 0xffff0000, v212
	v_lshlrev_b32_e32 v148, 16, v213
	v_and_b32_e32 v149, 0xffff0000, v213
	v_mul_f32_e32 v142, v142, v168
	v_mul_f32_e32 v143, v143, v168
	v_mul_f32_e32 v144, v144, v168
	v_mul_f32_e32 v145, v145, v168
	v_mul_f32_e32 v146, v146, v168
	v_mul_f32_e32 v147, v147, v168
	v_mul_f32_e32 v148, v148, v168
	v_mul_f32_e32 v149, v149, v168
	v_mul_f32_e32 v142, v142, v126
	v_mul_f32_e32 v143, v143, v127
	v_mul_f32_e32 v144, v144, v128
	v_mul_f32_e32 v145, v145, v129
	v_mul_f32_e32 v146, v146, v130
	v_mul_f32_e32 v147, v147, v131
	v_mul_f32_e32 v148, v148, v132
	v_mul_f32_e32 v149, v149, v133
	v_cvt_pk_bf16_f32 v150, v142, v143
	v_cvt_pk_bf16_f32 v151, v144, v145
	v_cvt_pk_bf16_f32 v152, v146, v147
	v_cvt_pk_bf16_f32 v153, v148, v149
	global_store_dwordx4 v169, v[150:153], s[6:7] offset:0
	s_nop 1
	v_readlane_b32 s76, v251, 57
	v_readlane_b32 s77, v251, 58
	v_readlane_b32 s52, v251, 61
	v_readlane_b32 s78, v253, 42
	v_readlane_b32 s53, v251, 62
	v_readlane_b32 s72, v251, 59
	v_readlane_b32 s79, v253, 43
	v_readlane_b32 s51, v251, 63
	v_readlane_b32 s54, v251, 0
	v_readlane_b32 s73, v251, 60
	s_mul_i32 s55, s82, 24
	v_readlane_b32 s74, v253, 27
	v_readlane_b32 s75, v253, 28
	v_readlane_b32 s79, v253, 29
	v_readlane_b32 s83, v253, 30
	v_readlane_b32 s53, v253, 26
	s_nop 4
	s_branch .LBB0_1129

; __device__ __forceinline__ unsigned xb_ld(unsigned* p)              { return __hip_atomic_load(p, __ATOMIC_RELAXED, __HIP_MEMORY_SCOPE_AGENT); }
; __device__ __forceinline__ unsigned xb_add(unsigned* p, unsigned v) { return __hip_atomic_fetch_add(p, v, __ATOMIC_RELAXED, __HIP_MEMORY_SCOPE_AGENT); }
; #define XB_SPIN(cond, bar) do { unsigned _sp = 0; while (cond) { __builtin_amdgcn_s_sleep(1); \
;     if ((++_sp & 255u) == 0u) { if (xb_ld(&(bar)[XB_TMO])) break; if (_sp > XB_SPIN_CAP) { atomicAdd(&(bar)[XB_TMO], 1u); break; } } } } while (0)
; __device__ __forceinline__ void xcd_barrier(const XcdBarrier& b) {
;     asm volatile("s_waitcnt vmcnt(0)" ::: "memory");
;     __syncthreads();
;     if (threadIdx.x == 0) {
;         unsigned* bar = b.bar;
;         __builtin_amdgcn_s_waitcnt(0);
;         unsigned nloc = b.st[0], nx = b.st[1];
;         if (nloc == 0u) { xcd_barrier_complete(bar, b.x, nloc, nx); b.st[0] = nloc; b.st[1] = nx; }
;         const unsigned old = xb_add(&bar[XB_XSUB(b.x)], 1u);
;         const unsigned gen = old / nloc;
;         if (old + 1u == (gen + 1u) * nloc) {
;             __builtin_amdgcn_fence(__ATOMIC_RELEASE, "agent");
;             asm volatile("s_waitcnt vmcnt(0)" ::: "memory");
;             const unsigned og = xb_add(&bar[XB_TOP], 1u);
;             const unsigned tg = og / nx;
;             if (og + 1u == (tg + 1u) * nx) xb_add(&bar[XB_TOPGEN], 1u);
;             else XB_SPIN(xb_ld(&bar[XB_TOPGEN]) == tg, bar);
;             __builtin_amdgcn_fence(__ATOMIC_ACQUIRE, "agent");
;             xb_add(&bar[XB_XGEN(b.x)], 1u);
;             asm volatile("s_waitcnt vmcnt(0)" ::: "memory");
;         } else {
;             XB_SPIN(xb_ld(&bar[XB_XGEN(b.x)]) == gen, bar);
.LBB0_1234:
	s_getreg_b32 s2, hwreg(HW_REG_XCC_ID, 0, 4)
	s_waitcnt vmcnt(0)
	s_waitcnt lgkmcnt(0)
	s_barrier
	s_and_b32 s32, s32, -2
	s_add_u32 s32, s32, 0x100
	s_and_saveexec_b64 s[4:5], s[76:77]
	s_cbranch_execz .Lfb9_skip
	s_add_u32 s8, s80, 0x101e4
	s_addc_u32 s9, s81, 0
	v_mov_b32_e32 v0, 0
	v_mov_b32_e32 v1, 1
	global_atomic_add v0, v1, s[8:9]
	v_mov_b32_e32 v0, 0x23ff8
	ds_read_b32 v2, v0
	s_waitcnt lgkmcnt(0)
	v_readfirstlane_b32 s3, v2
	s_cmp_eq_u32 s3, 1
	s_cbranch_scc0 .LBB0_1235
	v_readlane_b32 s3, v251, 0
	s_and_b32 s6, s3, 7
	s_lshl_b32 s6, s6, 5
	s_add_u32 s8, s80, 0x10040
	s_addc_u32 s9, s81, 0
	s_add_u32 s8, s8, s6
	s_addc_u32 s9, s9, 0
	v_mov_b32_e32 v0, 0
	v_mov_b32_e32 v1, 1
	global_atomic_add v2, v0, v1, s[8:9] sc0
	s_waitcnt vmcnt(0)
	v_readfirstlane_b32 s3, v2
	s_lshr_b32 s7, s3, 5
	s_add_i32 s7, s7, 1
	s_lshl_b32 s7, s7, 5
	s_and_b32 s3, s3, 31
	s_cmp_eq_u32 s3, 31
	s_cbranch_scc0 .Lfb9_spin0
	s_branch .Lfb9_rel
